# chip-wide + local seam split, plus GEMM prologue issuing K-tile 1 together with K-tile 0
# baseline (speedup 1.0000x reference)
.Lcb_done_g:
	s_add_i32 m0, s9, 0x10000
	v_add_u32_e32 v0, v16, v17
	v_mul_lo_u32 v1, v1, s52
	global_load_lds_dwordx4 v96, s[78:79]
	s_add_i32 m0, s9, 0x12000
	v_add_lshl_u32 v134, v1, v0, 1
	s_add_u32 s40, s78, s34
	global_load_lds_dwordx4 v134, s[78:79]
	s_addc_u32 s41, s79, s35
	s_add_i32 m0, s9, 0x14000
	s_mul_i32 s42, s72, s46
	global_load_lds_dwordx4 v96, s[40:41]
	s_add_i32 m0, s9, 0x16000
	v_readlane_b32 s48, v232, 4
	v_readlane_b32 s49, v232, 5
	s_add_u32 s42, s48, s42
	s_addc_u32 s43, s49, s43
	s_add_i32 s98, s9, 0x2000
	v_mul_lo_u32 v18, v2, s52
	global_load_lds_dwordx4 v134, s[40:41]
	s_mov_b32 m0, s9
	s_add_u32 s48, s42, s34
	v_add_lshl_u32 v132, v0, v18, 1
	global_load_lds_dwordx4 v130, s[42:43]
	s_mov_b32 m0, s98
	s_addc_u32 s49, s43, s35
	s_add_i32 s99, s9, 0x4000
	global_load_lds_dwordx4 v132, s[42:43]
	s_mov_b32 m0, s99
	s_add_i32 s76, s9, 0x6000
	global_load_lds_dwordx4 v130, s[48:49]
	s_mov_b32 m0, s76
	v_mov_b32_e32 v135, v97
	global_load_lds_dwordx4 v132, s[48:49]
	s_cmp_eq_u32 s1, 1
	v_lshl_add_u64 v[2:3], s[40:41], 0, v[96:97]
	v_lshl_add_u64 v[0:1], s[40:41], 0, v[134:135]
	v_mov_b32_e32 v131, v97
	v_mov_b32_e32 v133, v97
	s_cselect_b64 s[40:41], -1, 0
	v_lshl_add_u64 v[8:9], s[78:79], 0, v[96:97]
	v_lshl_add_u64 v[4:5], s[78:79], 0, v[134:135]
	v_lshl_add_u64 v[6:7], s[42:43], 0, v[130:131]
	v_writelane_b32 v232, s40, 6
	v_lshl_add_u64 v[10:11], s[42:43], 0, v[132:133]
	v_writelane_b32 v232, s41, 7
	s_add_i32 m0, s9, 0x18000
	v_lshl_add_u64 v[8:9], v[8:9], 0, s[12:13]
	global_load_lds_dwordx4 v[8:9], off
	v_lshl_add_u64 v[4:5], v[4:5], 0, s[12:13]
	s_add_i32 m0, s9, 0x1a000
	s_add_i32 s77, s9, 0x8000
	global_load_lds_dwordx4 v[4:5], off
	v_lshl_add_u64 v[4:5], v[6:7], 0, s[12:13]
	s_mov_b32 m0, s77
	s_add_i32 s86, s9, 0xa000
	global_load_lds_dwordx4 v[4:5], off
	v_lshl_add_u64 v[4:5], v[10:11], 0, s[12:13]
	s_mov_b32 m0, s86
	v_lshl_add_u64 v[2:3], v[2:3], 0, s[12:13]
	global_load_lds_dwordx4 v[4:5], off
	s_add_i32 m0, s9, 0x1c000
	v_lshl_add_u64 v[0:1], v[0:1], 0, s[12:13]
	global_load_lds_dwordx4 v[2:3], off
	s_add_i32 m0, s9, 0x1e000
	s_and_b32 s48, s0, 3
	global_load_lds_dwordx4 v[0:1], off
	s_cmp_lg_u32 s1, 1
	s_cbranch_scc1 .LBB0_323
	s_barrier
